# v3 + P7 epilogue: the 8 per-row rms-scale loads issued up front with counted vmcnt instead of 8 serial load-wait-store round trips
# speedup vs baseline: 1.0069x; 1.0037x over previous
; __device__ __forceinline__ float sigm(float x) { return __builtin_amdgcn_rcpf(1.0f + __expf(-x)); }
; __device__ __forceinline__ u32x4 pack8(const f32x4& v0, const f32x4& v1) { u32x4 w; w.x = cvt_pk_bf16(v0[0], v0[1]); w.y = cvt_pk_bf16(v0[2], v0[3]); w.z = cvt_pk_bf16(v1[0], v1[1]); w.w = cvt_pk_bf16(v1[2], v1[3]); return w; }
;     __device__ __forceinline__ void operator()(const f32x4 (&acc)[2][2][4][2], const Unit& u, int wr, int wc, int fr, int fq) const {
;     ...
;             for (int m = 0; m < 4; ++m) {
;                 const int row = row0 + ai * HALF + m * 16;
;                 const float rs = ss ? rsqrtf(ss[row] * (1.0f / 1024.0f) + 1e-6f) : 1.0f;
;                 bf16_t* rowp = out + (size_t)row * ld + col0;
; #pragma unroll
;                 for (int bj = 0; bj < 2; ++bj) {
;                     f32x4 v0 = acc[ai][bj][m][0] * rs, v1 = acc[ai][bj][m][1] * rs;
;                     if (ACT == 3) {
; #pragma unroll
;                         for (int j = 0; j < 4; ++j) { v0[j] = sigm(v0[j]); v1[j] = sigm(v1[j]); }
;                     }
;                     *(u32x4*)(rowp + bj * HALF) = pack8(v0, v1);
;                 }
.LBB0_1174:
	v_lshl_add_u32 v138, s68, 8, v146
	v_ashrrev_i32_e32 v139, 31, v138
	v_lshl_add_u64 v[140:141], v[138:139], 2, s[22:23]
	global_load_dword v150, v[140:141], off
	global_load_dword v151, v[140:141], off offset:64
	global_load_dword v152, v[140:141], off offset:128
	global_load_dword v153, v[140:141], off offset:192
	global_load_dword v154, v[140:141], off offset:512
	global_load_dword v155, v[140:141], off offset:576
	global_load_dword v156, v[140:141], off offset:640
	global_load_dword v157, v[140:141], off offset:704
	v_lshl_or_b32 v144, s67, 8, v148
	v_ashrrev_i32_e32 v145, 31, v144
	v_lshlrev_b64 v[144:145], 1, v[144:145]
	s_mov_b32 s67, s66
	s_mov_b32 s68, s65
	s_mov_b64 s[48:49], s[44:45]
	s_mov_b64 s[50:51], s[36:37]
	v_mov_b64_e32 v[142:143], s[20:21]
	s_waitcnt vmcnt(7)
	v_fmamk_f32 v150, v150, 0x3a800000, v178
	v_cmp_gt_f32_e32 vcc, s33, v150
	v_mul_f32_e32 v174, 0x4b800000, v150
	s_nop 0
	v_cndmask_b32_e32 v150, v150, v174, vcc
	v_rsq_f32_e32 v150, v150
	s_nop 0
	v_mul_f32_e32 v174, 0x45800000, v150
	v_cndmask_b32_e32 v158, v150, v174, vcc
	v_mov_b32_e32 v175, v138
	v_mad_i64_i32 v[184:185], s[2:3], v175, s86, v[142:143]
	v_pk_mul_f32 v[120:121], v[120:121], v[158:159] op_sel_hi:[1,0]
	v_pk_mul_f32 v[122:123], v[122:123], v[158:159] op_sel_hi:[1,0]
	v_pk_mul_f32 v[124:125], v[124:125], v[158:159] op_sel_hi:[1,0]
	v_pk_mul_f32 v[126:127], v[126:127], v[158:159] op_sel_hi:[1,0]
	v_lshl_add_u64 v[184:185], v[184:185], 0, v[144:145]
	v_cvt_pk_bf16_f32 v188, v120, v121
	v_cvt_pk_bf16_f32 v189, v122, v123
	v_cvt_pk_bf16_f32 v190, v124, v125
	v_cvt_pk_bf16_f32 v191, v126, v127
	global_store_dwordx4 v[184:185], v[188:191], off
	v_pk_mul_f32 v[116:117], v[116:117], v[158:159] op_sel_hi:[1,0]
	v_pk_mul_f32 v[118:119], v[118:119], v[158:159] op_sel_hi:[1,0]
	v_pk_mul_f32 v[112:113], v[112:113], v[158:159] op_sel_hi:[1,0]
	v_pk_mul_f32 v[114:115], v[114:115], v[158:159] op_sel_hi:[1,0]
	v_cvt_pk_bf16_f32 v192, v116, v117
	v_cvt_pk_bf16_f32 v193, v118, v119
	v_cvt_pk_bf16_f32 v194, v112, v113
	v_cvt_pk_bf16_f32 v195, v114, v115
	global_store_dwordx4 v[184:185], v[192:195], off offset:256
	s_waitcnt vmcnt(8)
	v_fmamk_f32 v151, v151, 0x3a800000, v178
	v_cmp_gt_f32_e32 vcc, s33, v151
	v_mul_f32_e32 v174, 0x4b800000, v151
	s_nop 0
	v_cndmask_b32_e32 v151, v151, v174, vcc
	v_rsq_f32_e32 v151, v151
	s_nop 0
	v_mul_f32_e32 v174, 0x45800000, v151
	v_cndmask_b32_e32 v160, v151, v174, vcc
	v_add_u32_e32 v175, 16, v138
	v_mad_i64_i32 v[184:185], s[2:3], v175, s86, v[142:143]
	v_pk_mul_f32 v[108:109], v[108:109], v[160:161] op_sel_hi:[1,0]
	v_pk_mul_f32 v[110:111], v[110:111], v[160:161] op_sel_hi:[1,0]
	v_pk_mul_f32 v[104:105], v[104:105], v[160:161] op_sel_hi:[1,0]
	v_pk_mul_f32 v[106:107], v[106:107], v[160:161] op_sel_hi:[1,0]
	v_lshl_add_u64 v[184:185], v[184:185], 0, v[144:145]
	v_cvt_pk_bf16_f32 v196, v108, v109
	v_cvt_pk_bf16_f32 v197, v110, v111
	v_cvt_pk_bf16_f32 v198, v104, v105
	v_cvt_pk_bf16_f32 v199, v106, v107
	global_store_dwordx4 v[184:185], v[196:199], off
	v_pk_mul_f32 v[100:101], v[100:101], v[160:161] op_sel_hi:[1,0]
	v_pk_mul_f32 v[102:103], v[102:103], v[160:161] op_sel_hi:[1,0]
	v_pk_mul_f32 v[96:97], v[96:97], v[160:161] op_sel_hi:[1,0]
	v_pk_mul_f32 v[98:99], v[98:99], v[160:161] op_sel_hi:[1,0]
	v_cvt_pk_bf16_f32 v218, v100, v101
	v_cvt_pk_bf16_f32 v219, v102, v103
	v_cvt_pk_bf16_f32 v220, v96, v97
	v_cvt_pk_bf16_f32 v221, v98, v99
	global_store_dwordx4 v[184:185], v[218:221], off offset:256
	s_waitcnt vmcnt(9)
	v_fmamk_f32 v152, v152, 0x3a800000, v178
	v_cmp_gt_f32_e32 vcc, s33, v152
	v_mul_f32_e32 v174, 0x4b800000, v152
	s_nop 0
	v_cndmask_b32_e32 v152, v152, v174, vcc
	v_rsq_f32_e32 v152, v152
	s_nop 0
	v_mul_f32_e32 v174, 0x45800000, v152
	v_cndmask_b32_e32 v162, v152, v174, vcc
	v_add_u32_e32 v175, 32, v138
	v_mad_i64_i32 v[184:185], s[2:3], v175, s86, v[142:143]
	v_pk_mul_f32 v[92:93], v[92:93], v[162:163] op_sel_hi:[1,0]
	v_pk_mul_f32 v[94:95], v[94:95], v[162:163] op_sel_hi:[1,0]
	v_pk_mul_f32 v[88:89], v[88:89], v[162:163] op_sel_hi:[1,0]
	v_pk_mul_f32 v[90:91], v[90:91], v[162:163] op_sel_hi:[1,0]
	v_lshl_add_u64 v[184:185], v[184:185], 0, v[144:145]
	v_cvt_pk_bf16_f32 v188, v92, v93
	v_cvt_pk_bf16_f32 v189, v94, v95
	v_cvt_pk_bf16_f32 v190, v88, v89
	v_cvt_pk_bf16_f32 v191, v90, v91
	global_store_dwordx4 v[184:185], v[188:191], off
	v_pk_mul_f32 v[84:85], v[84:85], v[162:163] op_sel_hi:[1,0]
	v_pk_mul_f32 v[86:87], v[86:87], v[162:163] op_sel_hi:[1,0]
	v_pk_mul_f32 v[80:81], v[80:81], v[162:163] op_sel_hi:[1,0]
	v_pk_mul_f32 v[82:83], v[82:83], v[162:163] op_sel_hi:[1,0]
	v_cvt_pk_bf16_f32 v192, v84, v85
	v_cvt_pk_bf16_f32 v193, v86, v87
	v_cvt_pk_bf16_f32 v194, v80, v81
	v_cvt_pk_bf16_f32 v195, v82, v83
	global_store_dwordx4 v[184:185], v[192:195], off offset:256
	s_waitcnt vmcnt(10)
	v_fmamk_f32 v153, v153, 0x3a800000, v178
	v_cmp_gt_f32_e32 vcc, s33, v153
	v_mul_f32_e32 v174, 0x4b800000, v153
	s_nop 0
	v_cndmask_b32_e32 v153, v153, v174, vcc
	v_rsq_f32_e32 v153, v153
	s_nop 0
	v_mul_f32_e32 v174, 0x45800000, v153
	v_cndmask_b32_e32 v164, v153, v174, vcc
	v_add_u32_e32 v175, 48, v138
	v_mad_i64_i32 v[184:185], s[2:3], v175, s86, v[142:143]
	v_pk_mul_f32 v[76:77], v[76:77], v[164:165] op_sel_hi:[1,0]
	v_pk_mul_f32 v[78:79], v[78:79], v[164:165] op_sel_hi:[1,0]
	v_pk_mul_f32 v[72:73], v[72:73], v[164:165] op_sel_hi:[1,0]
	v_pk_mul_f32 v[74:75], v[74:75], v[164:165] op_sel_hi:[1,0]
	v_lshl_add_u64 v[184:185], v[184:185], 0, v[144:145]
	v_cvt_pk_bf16_f32 v196, v76, v77
	v_cvt_pk_bf16_f32 v197, v78, v79
	v_cvt_pk_bf16_f32 v198, v72, v73
	v_cvt_pk_bf16_f32 v199, v74, v75
	global_store_dwordx4 v[184:185], v[196:199], off
	v_pk_mul_f32 v[68:69], v[68:69], v[164:165] op_sel_hi:[1,0]
	v_pk_mul_f32 v[70:71], v[70:71], v[164:165] op_sel_hi:[1,0]
	v_pk_mul_f32 v[64:65], v[64:65], v[164:165] op_sel_hi:[1,0]
	v_pk_mul_f32 v[66:67], v[66:67], v[164:165] op_sel_hi:[1,0]
	v_cvt_pk_bf16_f32 v218, v68, v69
	v_cvt_pk_bf16_f32 v219, v70, v71
	v_cvt_pk_bf16_f32 v220, v64, v65
	v_cvt_pk_bf16_f32 v221, v66, v67
	global_store_dwordx4 v[184:185], v[218:221], off offset:256
	s_waitcnt vmcnt(11)
; __device__ __forceinline__ float sigm(float x) { return __builtin_amdgcn_rcpf(1.0f + __expf(-x)); }
; __device__ __forceinline__ u32x4 pack8(const f32x4& v0, const f32x4& v1) { u32x4 w; w.x = cvt_pk_bf16(v0[0], v0[1]); w.y = cvt_pk_bf16(v0[2], v0[3]); w.z = cvt_pk_bf16(v1[0], v1[1]); w.w = cvt_pk_bf16(v1[2], v1[3]); return w; }
;     __device__ __forceinline__ void operator()(const f32x4 (&acc)[2][2][4][2], const Unit& u, int wr, int wc, int fr, int fq) const {
;     ...
;             for (int m = 0; m < 4; ++m) {
;                 const int row = row0 + ai * HALF + m * 16;
;                 const float rs = ss ? rsqrtf(ss[row] * (1.0f / 1024.0f) + 1e-6f) : 1.0f;
;                 bf16_t* rowp = out + (size_t)row * ld + col0;
; #pragma unroll
;                 for (int bj = 0; bj < 2; ++bj) {
;                     f32x4 v0 = acc[ai][bj][m][0] * rs, v1 = acc[ai][bj][m][1] * rs;
;                     if (ACT == 3) {
; #pragma unroll
;                         for (int j = 0; j < 4; ++j) { v0[j] = sigm(v0[j]); v1[j] = sigm(v1[j]); }
;                     }
;                     *(u32x4*)(rowp + bj * HALF) = pack8(v0, v1);
;                 }
	v_fmamk_f32 v154, v154, 0x3a800000, v178
	v_cmp_gt_f32_e32 vcc, s33, v154
	v_mul_f32_e32 v174, 0x4b800000, v154
	s_nop 0
	v_cndmask_b32_e32 v154, v154, v174, vcc
	v_rsq_f32_e32 v154, v154
	s_nop 0
	v_mul_f32_e32 v174, 0x45800000, v154
	v_cndmask_b32_e32 v166, v154, v174, vcc
	v_add_u32_e32 v175, 128, v138
	v_mad_i64_i32 v[184:185], s[2:3], v175, s86, v[142:143]
	v_pk_mul_f32 v[60:61], v[60:61], v[166:167] op_sel_hi:[1,0]
	v_pk_mul_f32 v[62:63], v[62:63], v[166:167] op_sel_hi:[1,0]
	v_pk_mul_f32 v[56:57], v[56:57], v[166:167] op_sel_hi:[1,0]
	v_pk_mul_f32 v[58:59], v[58:59], v[166:167] op_sel_hi:[1,0]
	v_lshl_add_u64 v[184:185], v[184:185], 0, v[144:145]
	v_cvt_pk_bf16_f32 v188, v60, v61
	v_cvt_pk_bf16_f32 v189, v62, v63
	v_cvt_pk_bf16_f32 v190, v56, v57
	v_cvt_pk_bf16_f32 v191, v58, v59
	global_store_dwordx4 v[184:185], v[188:191], off
	v_pk_mul_f32 v[52:53], v[52:53], v[166:167] op_sel_hi:[1,0]
	v_pk_mul_f32 v[54:55], v[54:55], v[166:167] op_sel_hi:[1,0]
	v_pk_mul_f32 v[48:49], v[48:49], v[166:167] op_sel_hi:[1,0]
	v_pk_mul_f32 v[50:51], v[50:51], v[166:167] op_sel_hi:[1,0]
	v_cvt_pk_bf16_f32 v192, v52, v53
	v_cvt_pk_bf16_f32 v193, v54, v55
	v_cvt_pk_bf16_f32 v194, v48, v49
	v_cvt_pk_bf16_f32 v195, v50, v51
	global_store_dwordx4 v[184:185], v[192:195], off offset:256
	s_waitcnt vmcnt(12)
	v_fmamk_f32 v155, v155, 0x3a800000, v178
	v_cmp_gt_f32_e32 vcc, s33, v155
	v_mul_f32_e32 v174, 0x4b800000, v155
	s_nop 0
	v_cndmask_b32_e32 v155, v155, v174, vcc
	v_rsq_f32_e32 v155, v155
	s_nop 0
	v_mul_f32_e32 v174, 0x45800000, v155
	v_cndmask_b32_e32 v168, v155, v174, vcc
	v_add_u32_e32 v175, 144, v138
	v_mad_i64_i32 v[184:185], s[2:3], v175, s86, v[142:143]
	v_pk_mul_f32 v[44:45], v[44:45], v[168:169] op_sel_hi:[1,0]
	v_pk_mul_f32 v[46:47], v[46:47], v[168:169] op_sel_hi:[1,0]
	v_pk_mul_f32 v[40:41], v[40:41], v[168:169] op_sel_hi:[1,0]
	v_pk_mul_f32 v[42:43], v[42:43], v[168:169] op_sel_hi:[1,0]
	v_lshl_add_u64 v[184:185], v[184:185], 0, v[144:145]
	v_cvt_pk_bf16_f32 v196, v44, v45
	v_cvt_pk_bf16_f32 v197, v46, v47
	v_cvt_pk_bf16_f32 v198, v40, v41
	v_cvt_pk_bf16_f32 v199, v42, v43
	global_store_dwordx4 v[184:185], v[196:199], off
	v_pk_mul_f32 v[36:37], v[36:37], v[168:169] op_sel_hi:[1,0]
	v_pk_mul_f32 v[38:39], v[38:39], v[168:169] op_sel_hi:[1,0]
	v_pk_mul_f32 v[32:33], v[32:33], v[168:169] op_sel_hi:[1,0]
	v_pk_mul_f32 v[34:35], v[34:35], v[168:169] op_sel_hi:[1,0]
	v_cvt_pk_bf16_f32 v218, v36, v37
	v_cvt_pk_bf16_f32 v219, v38, v39
	v_cvt_pk_bf16_f32 v220, v32, v33
	v_cvt_pk_bf16_f32 v221, v34, v35
	global_store_dwordx4 v[184:185], v[218:221], off offset:256
	s_waitcnt vmcnt(13)
	v_fmamk_f32 v156, v156, 0x3a800000, v178
	v_cmp_gt_f32_e32 vcc, s33, v156
	v_mul_f32_e32 v174, 0x4b800000, v156
	s_nop 0
	v_cndmask_b32_e32 v156, v156, v174, vcc
	v_rsq_f32_e32 v156, v156
	s_nop 0
	v_mul_f32_e32 v174, 0x45800000, v156
	v_cndmask_b32_e32 v170, v156, v174, vcc
	v_add_u32_e32 v175, 160, v138
	v_mad_i64_i32 v[184:185], s[2:3], v175, s86, v[142:143]
	v_pk_mul_f32 v[28:29], v[28:29], v[170:171] op_sel_hi:[1,0]
	v_pk_mul_f32 v[30:31], v[30:31], v[170:171] op_sel_hi:[1,0]
	v_pk_mul_f32 v[24:25], v[24:25], v[170:171] op_sel_hi:[1,0]
	v_pk_mul_f32 v[26:27], v[26:27], v[170:171] op_sel_hi:[1,0]
	v_lshl_add_u64 v[184:185], v[184:185], 0, v[144:145]
	v_cvt_pk_bf16_f32 v188, v28, v29
	v_cvt_pk_bf16_f32 v189, v30, v31
	v_cvt_pk_bf16_f32 v190, v24, v25
	v_cvt_pk_bf16_f32 v191, v26, v27
	global_store_dwordx4 v[184:185], v[188:191], off
	v_pk_mul_f32 v[20:21], v[20:21], v[170:171] op_sel_hi:[1,0]
	v_pk_mul_f32 v[22:23], v[22:23], v[170:171] op_sel_hi:[1,0]
	v_pk_mul_f32 v[16:17], v[16:17], v[170:171] op_sel_hi:[1,0]
	v_pk_mul_f32 v[18:19], v[18:19], v[170:171] op_sel_hi:[1,0]
	v_cvt_pk_bf16_f32 v192, v20, v21
	v_cvt_pk_bf16_f32 v193, v22, v23
	v_cvt_pk_bf16_f32 v194, v16, v17
	v_cvt_pk_bf16_f32 v195, v18, v19
	global_store_dwordx4 v[184:185], v[192:195], off offset:256
	s_waitcnt vmcnt(14)
	v_fmamk_f32 v157, v157, 0x3a800000, v178
	v_cmp_gt_f32_e32 vcc, s33, v157
	v_mul_f32_e32 v174, 0x4b800000, v157
	s_nop 0
	v_cndmask_b32_e32 v157, v157, v174, vcc
	v_rsq_f32_e32 v157, v157
	s_nop 0
	v_mul_f32_e32 v174, 0x45800000, v157
	v_cndmask_b32_e32 v172, v157, v174, vcc
	v_add_u32_e32 v175, 176, v138
	v_mad_i64_i32 v[184:185], s[2:3], v175, s86, v[142:143]
	v_pk_mul_f32 v[12:13], v[12:13], v[172:173] op_sel_hi:[1,0]
	v_pk_mul_f32 v[14:15], v[14:15], v[172:173] op_sel_hi:[1,0]
	v_pk_mul_f32 v[8:9], v[8:9], v[172:173] op_sel_hi:[1,0]
	v_pk_mul_f32 v[10:11], v[10:11], v[172:173] op_sel_hi:[1,0]
	v_lshl_add_u64 v[184:185], v[184:185], 0, v[144:145]
	v_cvt_pk_bf16_f32 v196, v12, v13
	v_cvt_pk_bf16_f32 v197, v14, v15
	v_cvt_pk_bf16_f32 v198, v8, v9
	v_cvt_pk_bf16_f32 v199, v10, v11
	global_store_dwordx4 v[184:185], v[196:199], off
	v_pk_mul_f32 v[4:5], v[4:5], v[172:173] op_sel_hi:[1,0]
	v_pk_mul_f32 v[6:7], v[6:7], v[172:173] op_sel_hi:[1,0]
	v_pk_mul_f32 v[0:1], v[0:1], v[172:173] op_sel_hi:[1,0]
	v_pk_mul_f32 v[2:3], v[2:3], v[172:173] op_sel_hi:[1,0]
	v_cvt_pk_bf16_f32 v218, v4, v5
	v_cvt_pk_bf16_f32 v219, v6, v7
	v_cvt_pk_bf16_f32 v220, v0, v1
	v_cvt_pk_bf16_f32 v221, v2, v3
	global_store_dwordx4 v[184:185], v[218:221], off offset:256
	s_and_b64 vcc, exec, s[42:43]
	s_cbranch_vccnz .LBB0_1184
